# code placement 2: also the mini-GEMM, row-pass, cache_tail and attention item loop heads aligned to 64 B
# speedup vs baseline: 1.0101x; 1.0001x over previous
.LBB0_416:
	s_add_i32 s26, s28, s33
	s_lshl_b32 s26, s26, 3
	s_add_i32 s38, s26, s70
	s_cmpk_lt_i32 s38, 0x2200
	s_cbranch_scc0 .LBB0_440
	.p2align	6

.LBB0_500:
	s_add_i32 s13, s13, s33
	s_waitcnt lgkmcnt(0)
	s_lshl_b32 s6, s13, 3
	s_or_b32 s25, s6, s62
	s_cmpk_lt_i32 s25, 0x2200
	s_cbranch_scc0 .LBB0_581
	.p2align	6

.LBB0_652:
	s_cmpk_gt_u32 s2, 0xff
	s_waitcnt vmcnt(0)
	v_mov_b32_e32 v6, v184
	s_cbranch_scc1 .LBB0_655
	v_and_b32_e32 v2, 0x70, v6
	v_mov_b32_e32 v3, 0
	s_lshl_b32 s4, s2, 1
	v_lshl_add_u64 v[4:5], s[10:11], 0, v[2:3]
	v_lshlrev_b32_e32 v2, 3, v6
	s_and_b32 s13, s4, 14
	s_lshl_b32 s4, s70, 7
	v_ashrrev_i32_e32 v7, 4, v6
	v_and_b32_e32 v2, 56, v2
	v_lshl_add_u32 v10, v7, 3, s4
	v_ashrrev_i32_e32 v8, 3, v6
	v_lshrrev_b32_e32 v9, 2, v2
	s_ashr_i32 s14, s33, 31
	v_lshl_add_u32 v12, s70, 3, v8
	v_and_b32_e32 v11, 7, v8
	v_bitop3_b32 v8, v9, v8, 7 bitop3:0x78
	v_add_u32_e32 v13, 64, v10
	s_lshl_b32 s5, s70, 14
	s_lshr_b32 s14, s14, 29
	v_lshlrev_b32_e32 v25, 4, v8
	v_bitop3_b32 v8, v9, v11, 1 bitop3:0x36
	v_ashrrev_i32_e32 v14, 6, v13
	v_bitop3_b32 v13, v7, v6, 7 bitop3:0x78
	v_add_u32_e32 v17, 4, v7
	v_add_u32_e32 v19, 8, v7
	v_add_u32_e32 v7, 12, v7
	v_and_b32_e32 v1, 15, v6
	s_add_i32 s5, s5, 0
	s_add_i32 s14, s33, s14
	v_lshl_add_u32 v18, v12, 8, 0
	v_lshlrev_b32_e32 v26, 4, v8
	v_ashrrev_i32_e32 v8, 6, v10
	v_bitop3_b32 v17, v17, v6, 7 bitop3:0x78
	v_bitop3_b32 v19, v19, v6, 7 bitop3:0x78
	v_bitop3_b32 v6, v7, v6, 7 bitop3:0x78
	s_lshr_b32 s12, s2, 3
	s_ashr_i32 s14, s14, 3
	v_lshl_add_u32 v16, v1, 8, s5
	v_ashrrev_i32_e32 v9, 31, v8
	v_ashrrev_i32_e32 v11, 31, v10
	v_ashrrev_i32_e32 v15, 31, v14
	v_lshlrev_b32_e32 v13, 4, v13
	v_lshlrev_b32_e32 v17, 4, v17
	v_lshlrev_b32_e32 v19, 4, v19
	v_lshlrev_b32_e32 v20, 4, v6
	v_add_u32_e32 v21, 0x10000, v18
	v_add_u32_e32 v22, 0x14000, v18
	v_add_u32_e32 v24, 0x18000, v18
	v_add_u32_e32 v27, 0x1c000, v18
	s_mov_b32 s10, 0x10000
	s_mov_b32 s11, 0x18000
	v_lshlrev_b64 v[6:7], 7, v[8:9]
	v_lshlrev_b64 v[8:9], 7, v[14:15]
	v_lshl_add_u64 v[10:11], v[10:11], 1, s[8:9]
	s_lshl_b32 s8, s12, 6
	s_lshl_b32 s9, s14, 6
	s_mov_b32 s15, 0x8000
	v_add_u32_e32 v13, v16, v13
	v_add_u32_e32 v14, v16, v17
	v_add_u32_e32 v15, v16, v19
	v_add_u32_e32 v16, v16, v20
	v_add_u32_e32 v17, v18, v25
	v_add_u32_e32 v18, v18, v26
	v_add_u32_e32 v19, v21, v25
	v_add_u32_e32 v20, v21, v26
	v_add_u32_e32 v21, v22, v25
	v_add_u32_e32 v22, v22, v26
	v_add_u32_e32 v23, v24, v25
	v_add_u32_e32 v24, v24, v26
	v_add_u32_e32 v25, v27, v25
	v_add_u32_e32 v26, v27, v26
	v_lshlrev_b32_e32 v2, 1, v2
	.p2align	6

.LBB0_719:
	s_add_u32 s14, s14, 4
	s_addc_u32 s15, s15, 0
	s_add_i32 s6, s10, s14
	s_add_u32 s13, s13, 16
	s_addc_u32 s36, s36, 0
	s_add_i32 s37, s37, -4
	s_cmp_lt_i32 s6, s12
	v_lshl_add_u64 v[84:85], v[84:85], 0, s[20:21]
	s_cbranch_scc0 .LBB0_743
	.p2align	6

.LBB0_852:
	s_add_u32 s6, s8, s6
	v_add_u32_e32 v36, s4, v20
	s_addc_u32 s7, s9, s7
	s_and_b32 s4, s17, 15
	s_mul_i32 s4, s4, 0x8400
	v_ashrrev_i32_e32 v37, 31, v36
	v_lshl_add_u64 v[36:37], v[36:37], 0, s[4:5]
	v_lshlrev_b64 v[36:37], 7, v[36:37]
	v_lshl_add_u64 v[36:37], s[6:7], 0, v[36:37]
	v_lshl_add_u64 v[40:41], v[36:37], 0, v[2:3]
	v_cvt_pk_bf16_f32 v36, v18, v19
	v_cvt_pk_bf16_f32 v37, v14, v15
	v_cvt_pk_bf16_f32 v38, v16, v17
	v_cvt_pk_bf16_f32 v39, v12, v13
	s_add_i32 s14, s14, s16
	global_store_dwordx4 v[40:41], v[36:39], off sc0 sc1
	s_nop 1
	s_cmp_lt_i32 s14, 64
	v_add_u32_e32 v21, s10, v21
	s_cbranch_scc0 .LBB0_855
	.p2align	6

.LBB0_1014:
	s_cmpk_gt_u32 s2, 0xff
	s_waitcnt vmcnt(0)
	v_mov_b32_e32 v4, v184
	s_cbranch_scc1 .LBB0_1017
	v_and_b32_e32 v0, 0x70, v4
	v_mov_b32_e32 v1, 0
	v_lshl_add_u64 v[2:3], s[10:11], 0, v[0:1]
	v_lshlrev_b32_e32 v0, 3, v4
	s_lshr_b32 s4, s2, 3
	s_lshl_b32 s2, s2, 1
	v_and_b32_e32 v0, 56, v0
	s_and_b32 s5, s2, 14
	s_lshl_b32 s2, s70, 7
	s_ashr_i32 s12, s33, 31
	v_ashrrev_i32_e32 v5, 4, v4
	v_ashrrev_i32_e32 v6, 3, v4
	v_lshrrev_b32_e32 v7, 2, v0
	s_lshl_b32 s3, s70, 14
	s_lshr_b32 s12, s12, 29
	v_lshl_add_u32 v8, v5, 3, s2
	v_lshl_add_u32 v11, s70, 3, v6
	v_and_b32_e32 v9, 7, v6
	v_bitop3_b32 v6, v7, v6, 7 bitop3:0x78
	v_bitop3_b32 v12, v5, v4, 7 bitop3:0x78
	v_add_u32_e32 v13, 4, v5
	v_add_u32_e32 v14, 8, v5
	v_add_u32_e32 v5, 12, v5
	v_and_b32_e32 v10, 15, v4
	s_add_i32 s3, s3, 0
	s_add_i32 s12, s33, s12
	v_lshl_add_u32 v17, v11, 8, 0
	v_lshlrev_b32_e32 v24, 4, v6
	v_bitop3_b32 v6, v7, v9, 1 bitop3:0x36
	v_add_u32_e32 v7, 64, v8
	v_bitop3_b32 v13, v13, v4, 7 bitop3:0x78
	v_bitop3_b32 v14, v14, v4, 7 bitop3:0x78
	v_bitop3_b32 v4, v5, v4, 7 bitop3:0x78
	s_ashr_i32 s12, s12, 3
	v_lshl_add_u32 v15, v10, 8, s3
	v_lshlrev_b32_e32 v25, 4, v6
	v_ashrrev_i32_e32 v6, 6, v8
	v_ashrrev_i32_e32 v9, 31, v8
	v_ashrrev_i32_e32 v7, 6, v7
	v_lshlrev_b32_e32 v12, 4, v12
	v_lshlrev_b32_e32 v13, 4, v13
	v_lshlrev_b32_e32 v14, 4, v14
	v_lshlrev_b32_e32 v16, 4, v4
	v_add_u32_e32 v19, 0x10000, v17
	v_add_u32_e32 v21, 0x14000, v17
	v_add_u32_e32 v23, 0x18000, v17
	v_add_u32_e32 v26, 0x1c000, v17
	s_mov_b32 s13, 0x420000
	s_mov_b32 s10, 0x10000
	s_mov_b32 s11, 0x18000
	v_mad_i64_i32 v[4:5], s[2:3], v6, s13, 0
	v_mad_i64_i32 v[6:7], s[2:3], v7, s13, 0
	v_lshl_add_u64 v[8:9], v[8:9], 1, s[8:9]
	s_lshl_b32 s8, s4, 6
	s_lshl_b32 s9, s12, 6
	s_mov_b32 s13, 0x8000
	s_movk_i32 s14, 0x1000
	v_add_u32_e32 v12, v15, v12
	v_add_u32_e32 v13, v15, v13
	v_add_u32_e32 v14, v15, v14
	v_add_u32_e32 v15, v15, v16
	v_add_u32_e32 v16, v17, v24
	v_add_u32_e32 v17, v17, v25
	v_add_u32_e32 v18, v19, v24
	v_add_u32_e32 v19, v19, v25
	v_add_u32_e32 v20, v21, v24
	v_add_u32_e32 v21, v21, v25
	v_add_u32_e32 v22, v23, v24
	v_add_u32_e32 v23, v23, v25
	v_add_u32_e32 v24, v26, v24
	v_add_u32_e32 v25, v26, v25
	v_lshlrev_b32_e32 v0, 1, v0
	.p2align	6

.LBB0_1080:
	s_add_u32 s5, s5, 16
	s_addc_u32 s28, s28, 0
	s_add_i32 s2, s8, 4
	s_add_i32 s3, s8, 3
	s_add_i32 s29, s29, -4
	v_lshl_add_u64 v[16:17], v[16:17], 0, s[18:19]
	v_lshl_add_u64 v[18:19], v[18:19], 0, s[20:21]
	s_cmp_lt_i32 s3, s4
	s_mov_b32 s8, s2
	s_cbranch_scc0 .LBB0_1097
	.p2align	6
